# plus Up conv epilogue VALU trim: in-place SDWA exp/rcp (no v_pack), v_fma_mix_f32 instead of cvt+cvt+pk_mul; hazards re-derived
# baseline (speedup 1.0000x reference)
;     __device__ __forceinline__ void operator()(const f32x4 (&acc)[2][2][4][2], const pg8::Unit& u, int ui, int wr, int wc, int fr, int fq) const {
;     ...
;             for (int m = 0; m < 4; ++m) {
;                 const int rl = ai * 128 + wr * 64 + m * 16 + fr;
;                 f32x4 a[2], o[2];
; #pragma unroll
;                 for (int n = 0; n < 2; ++n) {
;                     a[n] = acc[ai][0][m][n] * rr[ai][m];
;                     const f32x4 v = acc[ai][1][m][n] * rr[ai][m];
; #pragma unroll
;                     for (int q = 0; q < 2; ++q) {
;                         const int xb = __builtin_bit_cast(int, __builtin_amdgcn_cvt_pkrtz(a[n][2 * q], a[n][2 * q + 1]));
;                         const int t1 = __builtin_amdgcn_mov_dpp(xb, 0x121, 0xf, 0xf, true), t2 = __builtin_amdgcn_mov_dpp(xb, 0x122, 0xf, 0xf, true);
;                         const h2 p1 = __builtin_bit_cast(h2, (fr == 0) ? t1p[n][q] : t1), p2 = __builtin_bit_cast(h2, (fr < 2) ? t2p[n][q] : t2), x2 = __builtin_bit_cast(h2, xb);
;                         t1p[n][q] = t1; t2p[n][q] = t2;
;                         const h2 c = p2 * w0h[n][q] + (p1 * w1h[n][q] + (x2 * w2h[n][q] + bbh[n][q]));
;                         const h2 ea = c * (h2){(_Float16)(-LOG2E), (_Float16)(-LOG2E)};
;                         h2 ex; ex.x = __builtin_exp2f16(ea.x); ex.y = __builtin_exp2f16(ea.y);
;                         const h2 dn = ex + (h2){(_Float16)1.f, (_Float16)1.f};
;                         h2 rc; rc.x = __builtin_amdgcn_rcph(dn.x); rc.y = __builtin_amdgcn_rcph(dn.y);
;                         const h2 sg = c * rc;
;                         o[n][2 * q] = (float)sg.x * v[2 * q]; o[n][2 * q + 1] = (float)sg.y * v[2 * q + 1];
;                     }
;                 }
;                 u32x4 pk; pk.x = cvt_pk_bf16(o[0][0], o[0][1]); pk.y = cvt_pk_bf16(o[0][2], o[0][3]); pk.z = cvt_pk_bf16(o[1][0], o[1][1]); pk.w = cvt_pk_bf16(o[1][2], o[1][3]);
;                 *(u32x4*)(U + (size_t)(u.pm * 256 + rl) * FF + fcol) = pk;
;                 if (ai == 0 && m == 0 && wr == 0 && fr < 2) {
; #pragma unroll
;                     for (int n = 0; n < 2; ++n) { *(f32x4*)(topa + (size_t)(u.pm * 2 + fr) * FF + fcol + 4 * n) = a[n]; *(f32x4*)(topv + (size_t)(u.pm * 2 + fr) * FF + fcol + 4 * n) = acc[0][1][0][n] * rr[0][0]; }
;                 }
.LBB0_239:
	v_cvt_pk_f16_f32 v225, v146, v147
	v_cvt_pk_f16_f32 v146, v130, v131
	v_cvt_pk_f16_f32 v131, v136, v137
	s_waitcnt lgkmcnt(1)
	v_cvt_pkrtz_f16_f32 v136, v162, v163
	v_cvt_pk_f16_f32 v134, v134, v135
	v_cvt_pk_f16_f32 v135, v138, v139
	v_cvt_pk_f16_f32 v130, v132, v133
	v_cvt_pk_f16_f32 v132, v140, v141
	v_mov_b32_dpp v139, v136 row_ror:1 row_mask:0xf bank_mask:0xf bound_ctrl:1
	v_mov_b32_dpp v140, v136 row_ror:2 row_mask:0xf bank_mask:0xf bound_ctrl:1
	v_cvt_pkrtz_f16_f32 v136, v164, v165
	v_pk_mul_f32 v[126:127], v[126:127], v[204:205] op_sel_hi:[1,0]
	v_cvt_pk_f16_f32 v147, v148, v149
	v_cvt_pk_f16_f32 v148, v152, v153
	v_cvt_pk_f16_f32 v138, v142, v143
	v_mov_b32_dpp v141, v136 row_ror:1 row_mask:0xf bank_mask:0xf bound_ctrl:1
	v_mov_b32_dpp v142, v136 row_ror:2 row_mask:0xf bank_mask:0xf bound_ctrl:1
	s_waitcnt lgkmcnt(0)
	v_cvt_pkrtz_f16_f32 v136, v166, v167
	v_cvt_pkrtz_f16_f32 v152, v126, v127
	v_cvt_pk_f16_f32 v154, v154, v155
	v_cvt_pk_f16_f32 v155, v158, v159
	v_cvt_pk_f16_f32 v133, v144, v145
	v_mov_b32_dpp v143, v136 row_ror:1 row_mask:0xf bank_mask:0xf bound_ctrl:1
	v_mov_b32_dpp v144, v136 row_ror:2 row_mask:0xf bank_mask:0xf bound_ctrl:1
	v_mov_b32_dpp v136, v152 row_ror:1 row_mask:0xf bank_mask:0xf bound_ctrl:1
	v_cvt_pk_f16_f32 v151, v150, v151
	v_mov_b32_dpp v137, v152 row_ror:2 row_mask:0xf bank_mask:0xf bound_ctrl:1
	v_cndmask_b32_e64 v139, v136, v139, s[68:69]
	v_pk_fma_f16 v152, v154, v152, v155
	v_cndmask_b32_e64 v140, v137, v140, s[76:77]
	v_pk_fma_f16 v139, v151, v139, v152
	v_pk_mul_f32 v[128:129], v[128:129], v[204:205] op_sel_hi:[1,0]
	v_pk_fma_f16 v152, v225, v140, v139
	v_cvt_pk_f16_f32 v149, v156, v157
	v_pk_mul_f16 v139, v152, s52 op_sel_hi:[1,0]
	v_cvt_pkrtz_f16_f32 v157, v128, v129
	v_exp_f16_sdwa v139, v139 dst_sel:WORD_1 dst_unused:UNUSED_PRESERVE src0_sel:WORD_1
	s_nop 0
	v_exp_f16_sdwa v139, v139 dst_sel:WORD_0 dst_unused:UNUSED_PRESERVE src0_sel:WORD_0
	v_cvt_pk_f16_f32 v150, v160, v161
	v_pk_mul_f32 v[118:119], v[118:119], v[204:205] op_sel_hi:[1,0]
	v_pk_mul_f32 v[120:121], v[120:121], v[204:205] op_sel_hi:[1,0]
	v_pk_add_f16 v139, v139, 1.0 op_sel_hi:[1,0]
	v_mov_b32_dpp v140, v157 row_ror:2 row_mask:0xf bank_mask:0xf bound_ctrl:1
	v_rcp_f16_e32 v153, v139
	s_nop 0
	v_rcp_f16_sdwa v153, v139 dst_sel:WORD_1 dst_unused:UNUSED_PRESERVE src0_sel:WORD_1
	v_mov_b32_dpp v139, v157 row_ror:1 row_mask:0xf bank_mask:0xf bound_ctrl:1
	v_cndmask_b32_e64 v141, v139, v141, s[68:69]
	v_pk_fma_f16 v157, v149, v157, v150
	v_cndmask_b32_e64 v142, v140, v142, s[76:77]
	v_pk_fma_f16 v141, v148, v141, v157
	v_pk_fma_f16 v141, v147, v142, v141
	v_cvt_pkrtz_f16_f32 v145, v168, v169
	v_pk_mul_f16 v142, v141, s52 op_sel_hi:[1,0]
	v_cvt_pkrtz_f16_f32 v159, v120, v121
	v_exp_f16_sdwa v142, v142 dst_sel:WORD_1 dst_unused:UNUSED_PRESERVE src0_sel:WORD_1
	s_nop 0
	v_exp_f16_sdwa v142, v142 dst_sel:WORD_0 dst_unused:UNUSED_PRESERVE src0_sel:WORD_0
	v_mov_b32_dpp v158, v145 row_ror:1 row_mask:0xf bank_mask:0xf bound_ctrl:1
	v_mov_b32_dpp v145, v145 row_ror:2 row_mask:0xf bank_mask:0xf bound_ctrl:1
	v_pk_mul_f32 v[124:125], v[124:125], v[204:205] op_sel_hi:[1,0]
	v_pk_add_f16 v142, v142, 1.0 op_sel_hi:[1,0]
	v_pk_mul_f16 v153, v152, v153
	v_rcp_f16_sdwa v142, v142 dst_sel:WORD_1 dst_unused:UNUSED_PRESERVE src0_sel:WORD_1
	s_nop 0
	v_rcp_f16_sdwa v142, v142 dst_sel:WORD_0 dst_unused:UNUSED_PRESERVE src0_sel:WORD_0
	v_pk_mul_f32 v[122:123], v[122:123], v[204:205] op_sel_hi:[1,0]
	v_cvt_pkrtz_f16_f32 v156, v118, v119
	v_pk_mul_f16 v157, v141, v142
	v_fma_mix_f32 v152, v153, v122, 0 op_sel_hi:[1,0,0]
	v_fma_mix_f32 v153, v153, v123, 0 op_sel:[1,0,0] op_sel_hi:[1,0,0]
	v_mov_b32_dpp v141, v156 row_ror:1 row_mask:0xf bank_mask:0xf bound_ctrl:1
	v_mov_b32_dpp v142, v156 row_ror:2 row_mask:0xf bank_mask:0xf bound_ctrl:1
	v_cndmask_b32_e64 v143, v141, v143, s[68:69]
	v_pk_fma_f16 v156, v135, v156, v138
	v_cndmask_b32_e64 v144, v142, v144, s[76:77]
	v_pk_fma_f16 v143, v134, v143, v156
	v_pk_fma_f16 v160, v146, v144, v143
	v_pk_mul_f16 v143, v160, s52 op_sel_hi:[1,0]
	v_pk_mul_f32 v[114:115], v[114:115], v[204:205] op_sel_hi:[1,0]
	v_exp_f16_sdwa v143, v143 dst_sel:WORD_1 dst_unused:UNUSED_PRESERVE src0_sel:WORD_1
	s_nop 0
	v_exp_f16_sdwa v143, v143 dst_sel:WORD_0 dst_unused:UNUSED_PRESERVE src0_sel:WORD_0
	v_lshl_add_u32 v224, s40, 8, v206
	v_pk_mul_f32 v[116:117], v[116:117], v[204:205] op_sel_hi:[1,0]
	v_lshl_add_u32 v223, s40, 1, v1
	v_pk_add_f16 v143, v143, 1.0 op_sel_hi:[1,0]
	v_mov_b32_dpp v144, v159 row_ror:2 row_mask:0xf bank_mask:0xf bound_ctrl:1
	v_rcp_f16_e32 v161, v143
	v_rcp_f16_sdwa v162, v143 dst_sel:DWORD dst_unused:UNUSED_PAD src0_sel:WORD_1
	v_mov_b32_dpp v143, v159 row_ror:1 row_mask:0xf bank_mask:0xf bound_ctrl:1
	v_cndmask_b32_e64 v158, v143, v158, s[68:69]
	v_pk_fma_f16 v159, v132, v159, v133
	v_cndmask_b32_e64 v145, v144, v145, s[76:77]
	v_pk_fma_f16 v158, v131, v158, v159
	s_nop 0
	v_pk_fma_f16 v145, v130, v145, v158
	s_nop 0
	v_pk_mul_f16 v158, v145, s52 op_sel_hi:[1,0]
	s_nop 0
	v_exp_f16_e32 v163, v158
	v_exp_f16_sdwa v164, v158 dst_sel:DWORD dst_unused:UNUSED_PAD src0_sel:WORD_1
	v_fma_mix_f32 v158, v157, v124, 0 op_sel_hi:[1,0,0]
	v_fma_mix_f32 v159, v157, v125, 0 op_sel:[1,0,0] op_sel_hi:[1,0,0]
	v_pack_b32_f16 v156, v161, v162
	v_pack_b32_f16 v157, v163, v164
	v_pk_add_f16 v157, v157, 1.0 op_sel_hi:[1,0]
	s_nop 0
	v_rcp_f16_e32 v161, v157
	v_rcp_f16_sdwa v162, v157 dst_sel:DWORD dst_unused:UNUSED_PAD src0_sel:WORD_1
	v_pk_mul_f16 v157, v160, v156
	v_pack_b32_f16 v160, v161, v162
	v_pk_mul_f16 v145, v145, v160
	v_fma_mix_f32 v162, v157, v114, 0 op_sel_hi:[1,0,0]
	v_fma_mix_f32 v163, v157, v115, 0 op_sel:[1,0,0] op_sel_hi:[1,0,0]
	v_cvt_pk_bf16_f32 v156, v152, v153
	v_mov_b64_e32 v[152:153], s[50:51]
	v_mad_i64_i32 v[152:153], s[20:21], v224, s38, v[152:153]
	v_fma_mix_f32 v160, v145, v116, 0 op_sel_hi:[1,0,0]
	v_fma_mix_f32 v161, v145, v117, 0 op_sel:[1,0,0] op_sel_hi:[1,0,0]
	v_cvt_pk_bf16_f32 v157, v158, v159
	v_cvt_pk_bf16_f32 v158, v162, v163
	v_cvt_pk_bf16_f32 v159, v160, v161
	v_lshl_add_u64 v[152:153], v[194:195], 1, v[152:153]
	global_store_dwordx4 v[152:153], v[156:159], off
	s_and_saveexec_b64 s[20:21], s[18:19]
	s_cbranch_execz .LBB0_241
	s_movk_i32 s12, 0x2c00
	v_mov_b64_e32 v[156:157], s[58:59]
	v_mov_b64_e32 v[152:153], s[94:95]
	v_mad_i64_i32 v[156:157], s[18:19], v223, s12, v[156:157]
	v_mad_i64_i32 v[152:153], s[18:19], v223, s12, v[152:153]
	v_lshl_add_u64 v[156:157], v[156:157], 0, v[202:203]
	v_lshl_add_u64 v[152:153], v[152:153], 0, v[202:203]
	global_store_dwordx4 v[156:157], v[126:129], off
	global_store_dwordx4 v[152:153], v[122:125], off
	global_store_dwordx4 v[156:157], v[118:121], off offset:16
	global_store_dwordx4 v[152:153], v[114:117], off offset:16
; __device__ __forceinline__ unsigned cvt_pk_bf16(float lo, float hi) { const f32x2 v = {lo, hi}; const bf16x2_t b = __builtin_convertvector(v, bf16x2_t); return __builtin_bit_cast(unsigned, b); }
;     __device__ __forceinline__ void operator()(const f32x4 (&acc)[2][2][4][2], const pg8::Unit& u, int ui, int wr, int wc, int fr, int fq) const {
;     ...
;             for (int m = 0; m < 4; ++m) {
;                 const int rl = ai * 128 + wr * 64 + m * 16 + fr;
;                 f32x4 a[2], o[2];
; #pragma unroll
;                 for (int n = 0; n < 2; ++n) {
;                     a[n] = acc[ai][0][m][n] * rr[ai][m];
;                     const f32x4 v = acc[ai][1][m][n] * rr[ai][m];
; #pragma unroll
;                     for (int q = 0; q < 2; ++q) {
;                         const int xb = __builtin_bit_cast(int, __builtin_amdgcn_cvt_pkrtz(a[n][2 * q], a[n][2 * q + 1]));
;                         const int t1 = __builtin_amdgcn_mov_dpp(xb, 0x121, 0xf, 0xf, true), t2 = __builtin_amdgcn_mov_dpp(xb, 0x122, 0xf, 0xf, true);
;                         const h2 p1 = __builtin_bit_cast(h2, (fr == 0) ? t1p[n][q] : t1), p2 = __builtin_bit_cast(h2, (fr < 2) ? t2p[n][q] : t2), x2 = __builtin_bit_cast(h2, xb);
;                         t1p[n][q] = t1; t2p[n][q] = t2;
;                         const h2 c = p2 * w0h[n][q] + (p1 * w1h[n][q] + (x2 * w2h[n][q] + bbh[n][q]));
;                         const h2 ea = c * (h2){(_Float16)(-LOG2E), (_Float16)(-LOG2E)};
;                         h2 ex; ex.x = __builtin_exp2f16(ea.x); ex.y = __builtin_exp2f16(ea.y);
;                         const h2 dn = ex + (h2){(_Float16)1.f, (_Float16)1.f};
;                         h2 rc; rc.x = __builtin_amdgcn_rcph(dn.x); rc.y = __builtin_amdgcn_rcph(dn.y);
;                         const h2 sg = c * rc;
;                         o[n][2 * q] = (float)sg.x * v[2 * q]; o[n][2 * q + 1] = (float)sg.y * v[2 * q + 1];
;                     }
;                 }
;                 u32x4 pk; pk.x = cvt_pk_bf16(o[0][0], o[0][1]); pk.y = cvt_pk_bf16(o[0][2], o[0][3]); pk.z = cvt_pk_bf16(o[1][0], o[1][1]); pk.w = cvt_pk_bf16(o[1][2], o[1][3]);
;                 *(u32x4*)(U + (size_t)(u.pm * 256 + rl) * FF + fcol) = pk;
.LBB0_241:
	s_or_b64 exec, exec, s[20:21]
	s_nop 0
	v_mov_b32_e32 v114, v205
	v_pk_mul_f32 v[110:111], v[110:111], v[114:115] op_sel_hi:[1,0]
	v_pk_mul_f32 v[94:95], v[94:95], v[200:201] op_sel_hi:[1,0]
	v_cvt_pkrtz_f16_f32 v110, v110, v111
	v_cvt_pkrtz_f16_f32 v94, v94, v95
	v_pk_mul_f32 v[86:87], v[86:87], v[200:201] op_sel_hi:[1,0]
	v_mov_b32_dpp v115, v110 row_ror:1 row_mask:0xf bank_mask:0xf bound_ctrl:1
	v_mov_b32_dpp v116, v110 row_ror:2 row_mask:0xf bank_mask:0xf bound_ctrl:1
	v_cndmask_b32_e64 v111, v115, v136, s[68:69]
	v_pk_fma_f16 v110, v154, v110, v155
	v_cndmask_b32_e64 v117, v116, v137, s[76:77]
	v_pk_fma_f16 v110, v151, v111, v110
	v_pk_mul_f32 v[102:103], v[102:103], v[114:115] op_sel_hi:[1,0]
	v_pk_fma_f16 v117, v225, v117, v110
	v_cvt_pkrtz_f16_f32 v102, v102, v103
	v_pk_mul_f16 v110, v117, s52 op_sel_hi:[1,0]
	v_pk_mul_f32 v[104:105], v[104:105], v[114:115] op_sel_hi:[1,0]
	v_exp_f16_e32 v118, v110
	v_exp_f16_sdwa v119, v110 dst_sel:DWORD dst_unused:UNUSED_PAD src0_sel:WORD_1
	v_pk_mul_f32 v[110:111], v[112:113], v[114:115] op_sel_hi:[1,0]
	v_cvt_pkrtz_f16_f32 v104, v104, v105
	v_cvt_pkrtz_f16_f32 v110, v110, v111
	v_pack_b32_f16 v112, v118, v119
	v_pk_add_f16 v112, v112, 1.0 op_sel_hi:[1,0]
	v_mov_b32_dpp v118, v110 row_ror:1 row_mask:0xf bank_mask:0xf bound_ctrl:1
	v_mov_b32_dpp v119, v110 row_ror:2 row_mask:0xf bank_mask:0xf bound_ctrl:1
	v_cndmask_b32_e64 v111, v118, v139, s[68:69]
	v_pk_fma_f16 v110, v149, v110, v150
	v_cndmask_b32_e64 v120, v119, v140, s[76:77]
	v_pk_fma_f16 v110, v148, v111, v110
	v_rcp_f16_sdwa v112, v112 dst_sel:WORD_1 dst_unused:UNUSED_PRESERVE src0_sel:WORD_1
	v_pk_fma_f16 v120, v147, v120, v110
	v_rcp_f16_sdwa v112, v112 dst_sel:WORD_0 dst_unused:UNUSED_PRESERVE src0_sel:WORD_0
	v_pk_mul_f16 v110, v120, s52 op_sel_hi:[1,0]
	v_mov_b32_dpp v123, v104 row_ror:2 row_mask:0xf bank_mask:0xf bound_ctrl:1
	v_exp_f16_sdwa v110, v110 dst_sel:WORD_1 dst_unused:UNUSED_PRESERVE src0_sel:WORD_1
	s_nop 0
	v_exp_f16_sdwa v110, v110 dst_sel:WORD_0 dst_unused:UNUSED_PRESERVE src0_sel:WORD_0
	v_cndmask_b32_e64 v124, v123, v144, s[76:77]
	v_pk_mul_f32 v[108:109], v[108:109], v[114:115] op_sel_hi:[1,0]
	v_pk_add_f16 v110, v110, 1.0 op_sel_hi:[1,0]
	v_pk_mul_f16 v111, v117, v112
	v_rcp_f16_e32 v112, v110
	s_nop 0
	v_rcp_f16_sdwa v112, v110 dst_sel:WORD_1 dst_unused:UNUSED_PRESERVE src0_sel:WORD_1
	v_mov_b32_dpp v117, v102 row_ror:2 row_mask:0xf bank_mask:0xf bound_ctrl:1
	v_cvt_f32_f16_e32 v110, v111
	v_cvt_f32_f16_sdwa v111, v111 dst_sel:DWORD dst_unused:UNUSED_PAD src0_sel:WORD_1
	v_mov_b32_dpp v113, v102 row_ror:1 row_mask:0xf bank_mask:0xf bound_ctrl:1
	v_cndmask_b32_e64 v103, v113, v141, s[68:69]
	v_pk_fma_f16 v102, v135, v102, v138
	v_pk_mul_f16 v112, v120, v112
	v_cndmask_b32_e64 v120, v117, v142, s[76:77]
	v_pk_fma_f16 v102, v134, v103, v102
	v_cvt_f32_f16_sdwa v103, v112 dst_sel:DWORD dst_unused:UNUSED_PAD src0_sel:WORD_1
	v_pk_fma_f16 v120, v146, v120, v102
	v_pk_mul_f32 v[106:107], v[106:107], v[114:115] op_sel_hi:[1,0]
	v_pk_mul_f16 v102, v120, s52 op_sel_hi:[1,0]
	v_pk_mul_f32 v[100:101], v[100:101], v[114:115] op_sel_hi:[1,0]
	v_exp_f16_e32 v121, v102
	v_exp_f16_sdwa v122, v102 dst_sel:DWORD dst_unused:UNUSED_PAD src0_sel:WORD_1
	v_cvt_f32_f16_e32 v102, v112
	v_pk_mul_f32 v[98:99], v[98:99], v[114:115] op_sel_hi:[1,0]
	v_cvt_pkrtz_f16_f32 v86, v86, v87
	v_pack_b32_f16 v112, v121, v122
	v_mov_b32_dpp v122, v104 row_ror:1 row_mask:0xf bank_mask:0xf bound_ctrl:1
	v_cndmask_b32_e64 v105, v122, v143, s[68:69]
	v_pk_fma_f16 v104, v132, v104, v133
	v_pk_add_f16 v112, v112, 1.0 op_sel_hi:[1,0]
	v_pk_fma_f16 v104, v131, v105, v104
	v_rcp_f16_e32 v121, v112
	v_pk_fma_f16 v124, v130, v124, v104
	v_rcp_f16_sdwa v112, v112 dst_sel:DWORD dst_unused:UNUSED_PAD src0_sel:WORD_1
	v_pk_mul_f16 v104, v124, s52 op_sel_hi:[1,0]
	v_pk_mul_f32 v[88:89], v[88:89], v[200:201] op_sel_hi:[1,0]
	v_exp_f16_e32 v125, v104
	v_exp_f16_sdwa v126, v104 dst_sel:DWORD dst_unused:UNUSED_PAD src0_sel:WORD_1
	v_pk_mul_f32 v[104:105], v[106:107], v[110:111]
	v_pk_mul_f32 v[106:107], v[108:109], v[102:103]
	v_pack_b32_f16 v102, v121, v112
	v_pack_b32_f16 v103, v125, v126
	v_pk_add_f16 v103, v103, 1.0 op_sel_hi:[1,0]
	v_cvt_pkrtz_f16_f32 v88, v88, v89
	v_rcp_f16_e32 v108, v103
	s_nop 0
	v_rcp_f16_sdwa v108, v103 dst_sel:WORD_1 dst_unused:UNUSED_PRESERVE src0_sel:WORD_1
	v_pk_mul_f16 v103, v120, v102
	v_pk_mul_f32 v[90:91], v[90:91], v[200:201] op_sel_hi:[1,0]
	v_pk_mul_f16 v109, v124, v108
	v_pk_mul_f32 v[92:93], v[92:93], v[200:201] op_sel_hi:[1,0]
	v_fma_mix_f32 v98, v103, v98, 0 op_sel_hi:[1,0,0]
	v_fma_mix_f32 v99, v103, v99, 0 op_sel:[1,0,0] op_sel_hi:[1,0,0]
	v_cvt_pk_bf16_f32 v102, v104, v105
	v_fma_mix_f32 v100, v109, v100, 0 op_sel_hi:[1,0,0]
	v_fma_mix_f32 v101, v109, v101, 0 op_sel:[1,0,0] op_sel_hi:[1,0,0]
	v_mov_b32_dpp v108, v94 row_ror:1 row_mask:0xf bank_mask:0xf bound_ctrl:1
	v_mov_b32_dpp v109, v94 row_ror:2 row_mask:0xf bank_mask:0xf bound_ctrl:1
	v_cndmask_b32_e64 v95, v108, v115, s[68:69]
	v_pk_fma_f16 v94, v154, v94, v155
	v_cndmask_b32_e64 v110, v109, v116, s[76:77]
	v_pk_fma_f16 v94, v151, v95, v94
	v_cvt_pk_bf16_f32 v104, v98, v99
	v_cvt_pk_bf16_f32 v105, v100, v101
	v_or_b32_e32 v100, 16, v224
	v_mov_b64_e32 v[98:99], s[50:51]
	v_pk_fma_f16 v110, v225, v110, v94
	v_cvt_pk_bf16_f32 v103, v106, v107
	v_mad_i64_i32 v[106:107], s[18:19], v100, s38, v[98:99]
	v_lshlrev_b64 v[100:101], 1, v[194:195]
	v_pk_mul_f16 v94, v110, s52 op_sel_hi:[1,0]
	v_pk_mul_f32 v[82:83], v[82:83], v[200:201] op_sel_hi:[1,0]
	v_exp_f16_e32 v111, v94
	v_exp_f16_sdwa v112, v94 dst_sel:DWORD dst_unused:UNUSED_PAD src0_sel:WORD_1
; __device__ __forceinline__ unsigned cvt_pk_bf16(float lo, float hi) { const f32x2 v = {lo, hi}; const bf16x2_t b = __builtin_convertvector(v, bf16x2_t); return __builtin_bit_cast(unsigned, b); }
;     __device__ __forceinline__ void operator()(const f32x4 (&acc)[2][2][4][2], const pg8::Unit& u, int ui, int wr, int wc, int fr, int fq) const {
;     ...
;             for (int m = 0; m < 4; ++m) {
;                 const int rl = ai * 128 + wr * 64 + m * 16 + fr;
;                 f32x4 a[2], o[2];
; #pragma unroll
;                 for (int n = 0; n < 2; ++n) {
;                     a[n] = acc[ai][0][m][n] * rr[ai][m];
;                     const f32x4 v = acc[ai][1][m][n] * rr[ai][m];
; #pragma unroll
;                     for (int q = 0; q < 2; ++q) {
;                         const int xb = __builtin_bit_cast(int, __builtin_amdgcn_cvt_pkrtz(a[n][2 * q], a[n][2 * q + 1]));
;                         const int t1 = __builtin_amdgcn_mov_dpp(xb, 0x121, 0xf, 0xf, true), t2 = __builtin_amdgcn_mov_dpp(xb, 0x122, 0xf, 0xf, true);
;                         const h2 p1 = __builtin_bit_cast(h2, (fr == 0) ? t1p[n][q] : t1), p2 = __builtin_bit_cast(h2, (fr < 2) ? t2p[n][q] : t2), x2 = __builtin_bit_cast(h2, xb);
;                         t1p[n][q] = t1; t2p[n][q] = t2;
;                         const h2 c = p2 * w0h[n][q] + (p1 * w1h[n][q] + (x2 * w2h[n][q] + bbh[n][q]));
;                         const h2 ea = c * (h2){(_Float16)(-LOG2E), (_Float16)(-LOG2E)};
;                         h2 ex; ex.x = __builtin_exp2f16(ea.x); ex.y = __builtin_exp2f16(ea.y);
;                         const h2 dn = ex + (h2){(_Float16)1.f, (_Float16)1.f};
;                         h2 rc; rc.x = __builtin_amdgcn_rcph(dn.x); rc.y = __builtin_amdgcn_rcph(dn.y);
;                         const h2 sg = c * rc;
;                         o[n][2 * q] = (float)sg.x * v[2 * q]; o[n][2 * q + 1] = (float)sg.y * v[2 * q + 1];
;                     }
;                 }
;                 u32x4 pk; pk.x = cvt_pk_bf16(o[0][0], o[0][1]); pk.y = cvt_pk_bf16(o[0][2], o[0][3]); pk.z = cvt_pk_bf16(o[1][0], o[1][1]); pk.w = cvt_pk_bf16(o[1][2], o[1][3]);
;                 *(u32x4*)(U + (size_t)(u.pm * 256 + rl) * FF + fcol) = pk;
	v_lshl_add_u64 v[94:95], v[106:107], 0, v[100:101]
	global_store_dwordx4 v[94:95], v[102:105], off
	v_pk_mul_f32 v[94:95], v[96:97], v[200:201] op_sel_hi:[1,0]
	v_pack_b32_f16 v96, v111, v112
	v_cvt_pkrtz_f16_f32 v94, v94, v95
	v_pk_add_f16 v96, v96, 1.0 op_sel_hi:[1,0]
	v_pk_mul_f32 v[84:85], v[84:85], v[200:201] op_sel_hi:[1,0]
	v_mov_b32_dpp v102, v94 row_ror:1 row_mask:0xf bank_mask:0xf bound_ctrl:1
	v_mov_b32_dpp v103, v94 row_ror:2 row_mask:0xf bank_mask:0xf bound_ctrl:1
	v_cndmask_b32_e64 v95, v102, v118, s[68:69]
	v_pk_fma_f16 v94, v149, v94, v150
	v_cndmask_b32_e64 v104, v103, v119, s[76:77]
	v_pk_fma_f16 v94, v148, v95, v94
	v_rcp_f16_sdwa v96, v96 dst_sel:WORD_1 dst_unused:UNUSED_PRESERVE src0_sel:WORD_1
	v_pk_fma_f16 v104, v147, v104, v94
	v_rcp_f16_sdwa v96, v96 dst_sel:WORD_0 dst_unused:UNUSED_PRESERVE src0_sel:WORD_0
	v_pk_mul_f16 v94, v104, s52 op_sel_hi:[1,0]
	v_pk_mul_f32 v[62:63], v[62:63], v[198:199] op_sel_hi:[1,0]
	v_exp_f16_sdwa v94, v94 dst_sel:WORD_1 dst_unused:UNUSED_PRESERVE src0_sel:WORD_1
	s_nop 0
	v_exp_f16_sdwa v94, v94 dst_sel:WORD_0 dst_unused:UNUSED_PRESERVE src0_sel:WORD_0
	v_cvt_pkrtz_f16_f32 v62, v62, v63
	v_pk_mul_f32 v[54:55], v[54:55], v[198:199] op_sel_hi:[1,0]
	v_pk_add_f16 v94, v94, 1.0 op_sel_hi:[1,0]
	v_pk_mul_f16 v95, v110, v96
	v_rcp_f16_e32 v96, v94
	s_nop 0
	v_rcp_f16_sdwa v96, v94 dst_sel:WORD_1 dst_unused:UNUSED_PRESERVE src0_sel:WORD_1
	v_mov_b32_dpp v110, v88 row_ror:2 row_mask:0xf bank_mask:0xf bound_ctrl:1
	v_cndmask_b32_e64 v111, v110, v123, s[76:77]
	v_cvt_f32_f16_e32 v94, v95
	v_mov_b32_dpp v97, v86 row_ror:1 row_mask:0xf bank_mask:0xf bound_ctrl:1
	v_pk_mul_f16 v96, v104, v96
	v_mov_b32_dpp v104, v86 row_ror:2 row_mask:0xf bank_mask:0xf bound_ctrl:1
	v_cndmask_b32_e64 v87, v97, v113, s[68:69]
	v_pk_fma_f16 v86, v135, v86, v138
	v_cndmask_b32_e64 v105, v104, v117, s[76:77]
	v_pk_fma_f16 v86, v134, v87, v86
	v_cvt_f32_f16_sdwa v87, v96 dst_sel:DWORD dst_unused:UNUSED_PAD src0_sel:WORD_1
	v_pk_fma_f16 v105, v146, v105, v86
	v_cvt_f32_f16_sdwa v95, v95 dst_sel:DWORD dst_unused:UNUSED_PAD src0_sel:WORD_1
	v_pk_mul_f16 v86, v105, s52 op_sel_hi:[1,0]
	v_cvt_pkrtz_f16_f32 v54, v54, v55
	v_exp_f16_e32 v106, v86
	v_exp_f16_sdwa v107, v86 dst_sel:DWORD dst_unused:UNUSED_PAD src0_sel:WORD_1
	v_cvt_f32_f16_e32 v86, v96
	v_pk_mul_f32 v[56:57], v[56:57], v[198:199] op_sel_hi:[1,0]
	v_pk_mul_f32 v[58:59], v[58:59], v[198:199] op_sel_hi:[1,0]
	v_pack_b32_f16 v96, v106, v107
	v_mov_b32_dpp v107, v88 row_ror:1 row_mask:0xf bank_mask:0xf bound_ctrl:1
	v_cndmask_b32_e64 v89, v107, v122, s[68:69]
	v_pk_fma_f16 v88, v132, v88, v133
	v_pk_add_f16 v96, v96, 1.0 op_sel_hi:[1,0]
	v_pk_fma_f16 v88, v131, v89, v88
	v_rcp_f16_e32 v106, v96
	v_pk_fma_f16 v111, v130, v111, v88
	v_rcp_f16_sdwa v96, v96 dst_sel:DWORD dst_unused:UNUSED_PAD src0_sel:WORD_1
	v_pk_mul_f16 v88, v111, s52 op_sel_hi:[1,0]
	v_pk_mul_f32 v[86:87], v[92:93], v[86:87]
	v_exp_f16_e32 v112, v88
	v_exp_f16_sdwa v113, v88 dst_sel:DWORD dst_unused:UNUSED_PAD src0_sel:WORD_1
	v_pk_mul_f32 v[88:89], v[90:91], v[94:95]
	v_pack_b32_f16 v90, v106, v96
	v_cvt_pkrtz_f16_f32 v56, v56, v57
	v_pack_b32_f16 v91, v112, v113
	v_pk_add_f16 v91, v91, 1.0 op_sel_hi:[1,0]
	v_pk_mul_f32 v[60:61], v[60:61], v[198:199] op_sel_hi:[1,0]
	v_rcp_f16_e32 v92, v91
	s_nop 0
	v_rcp_f16_sdwa v92, v91 dst_sel:WORD_1 dst_unused:UNUSED_PRESERVE src0_sel:WORD_1
	v_pk_mul_f16 v91, v105, v90
	v_pk_mul_f32 v[50:51], v[50:51], v[198:199] op_sel_hi:[1,0]
	v_pk_mul_f16 v93, v111, v92
	v_pk_mul_f32 v[52:53], v[52:53], v[198:199] op_sel_hi:[1,0]
	v_fma_mix_f32 v90, v91, v82, 0 op_sel_hi:[1,0,0]
	v_fma_mix_f32 v91, v91, v83, 0 op_sel:[1,0,0] op_sel_hi:[1,0,0]
	v_cvt_pk_bf16_f32 v82, v88, v89
	v_mov_b32_e32 v88, v201
	v_pk_mul_f32 v[78:79], v[78:79], v[88:89] op_sel_hi:[1,0]
	v_cvt_pkrtz_f16_f32 v78, v78, v79
	v_cvt_pk_bf16_f32 v83, v86, v87
	s_nop 0
	v_mov_b32_dpp v79, v78 row_ror:1 row_mask:0xf bank_mask:0xf bound_ctrl:1
	v_mov_b32_dpp v89, v78 row_ror:2 row_mask:0xf bank_mask:0xf bound_ctrl:1
	v_cndmask_b32_e64 v79, v79, v108, s[68:69]
	v_pk_fma_f16 v78, v154, v78, v155
	v_cndmask_b32_e64 v89, v89, v109, s[76:77]
	v_pk_fma_f16 v78, v151, v79, v78
	v_or_b32_e32 v86, 32, v224
	v_pk_fma_f16 v89, v225, v89, v78
	v_fma_mix_f32 v92, v93, v84, 0 op_sel_hi:[1,0,0]
	v_fma_mix_f32 v93, v93, v85, 0 op_sel:[1,0,0] op_sel_hi:[1,0,0]
	v_mad_i64_i32 v[86:87], s[18:19], v86, s38, v[98:99]
	v_pk_mul_f16 v78, v89, s52 op_sel_hi:[1,0]
	v_cvt_pk_bf16_f32 v84, v90, v91
	v_cvt_pk_bf16_f32 v85, v92, v93
	v_exp_f16_e32 v90, v78
	v_exp_f16_sdwa v91, v78 dst_sel:DWORD dst_unused:UNUSED_PAD src0_sel:WORD_1
	v_lshl_add_u64 v[78:79], v[86:87], 0, v[100:101]
	global_store_dwordx4 v[78:79], v[82:85], off
	v_pk_mul_f32 v[78:79], v[80:81], v[88:89] op_sel_hi:[1,0]
	v_pack_b32_f16 v80, v90, v91
	v_cvt_pkrtz_f16_f32 v78, v78, v79
	v_pk_add_f16 v80, v80, 1.0 op_sel_hi:[1,0]
	v_pk_mul_f32 v[70:71], v[70:71], v[88:89] op_sel_hi:[1,0]
	v_mov_b32_dpp v79, v78 row_ror:1 row_mask:0xf bank_mask:0xf bound_ctrl:1
	v_mov_b32_dpp v82, v78 row_ror:2 row_mask:0xf bank_mask:0xf bound_ctrl:1
	v_cndmask_b32_e64 v79, v79, v102, s[68:69]
	v_pk_fma_f16 v78, v149, v78, v150
	v_cndmask_b32_e64 v82, v82, v103, s[76:77]
	v_pk_fma_f16 v78, v148, v79, v78
	v_rcp_f16_sdwa v80, v80 dst_sel:WORD_1 dst_unused:UNUSED_PRESERVE src0_sel:WORD_1
	v_pk_fma_f16 v82, v147, v82, v78
	v_rcp_f16_sdwa v80, v80 dst_sel:WORD_0 dst_unused:UNUSED_PRESERVE src0_sel:WORD_0
	v_pk_mul_f16 v78, v82, s52 op_sel_hi:[1,0]
	v_cvt_pkrtz_f16_f32 v70, v70, v71
	v_exp_f16_sdwa v78, v78 dst_sel:WORD_1 dst_unused:UNUSED_PRESERVE src0_sel:WORD_1
	s_nop 0
; #define LAS __attribute__((address_space(3)))
;     __device__ __forceinline__ void operator()(const f32x4 (&acc)[2][2][4][2], const pg8::Unit& u, int ui, int wr, int wc, int fr, int fq) const {
;     ...
;         for (int ai = 0; ai < 2; ++ai) {
;             f32x4 pv[2];
;             if (ai == 0 && wr == 0) { pv[0] = (f32x4){0.f, 0.f, 0.f, 0.f}; pv[1] = pv[0]; }
;             else { const int pai = (wr == 1) ? ai : ai - 1, pwr = wr ^ 1; const int xr = (fr >= 14) ? fr - 14 : 0;
; #pragma unroll
;                 for (int n = 0; n < 2; ++n) pv[n] = *(const LAS f32x4*)(xch + ((pai * 2 + pwr) * 4 + wc) * 64 + xr * 32 + 8 * fq + 4 * n); }
;             int t1p[2][2], t2p[2][2];
; #pragma unroll
;             for (int n = 0; n < 2; ++n)
; #pragma unroll
;                 for (int q = 0; q < 2; ++q) { const int pb = __builtin_bit_cast(int, __builtin_amdgcn_cvt_pkrtz(pv[n][2 * q], pv[n][2 * q + 1]));
;                     t1p[n][q] = __builtin_amdgcn_mov_dpp(pb, 0x121, 0xf, 0xf, true); t2p[n][q] = __builtin_amdgcn_mov_dpp(pb, 0x122, 0xf, 0xf, true); }
; #pragma unroll
;             for (int m = 0; m < 4; ++m) {
;                 const int rl = ai * 128 + wr * 64 + m * 16 + fr;
;                 f32x4 a[2], o[2];
; #pragma unroll
;                 for (int n = 0; n < 2; ++n) {
;                     a[n] = acc[ai][0][m][n] * rr[ai][m];
;                     const f32x4 v = acc[ai][1][m][n] * rr[ai][m];
; #pragma unroll
;                     for (int q = 0; q < 2; ++q) {
;                         const int xb = __builtin_bit_cast(int, __builtin_amdgcn_cvt_pkrtz(a[n][2 * q], a[n][2 * q + 1]));
;                         const int t1 = __builtin_amdgcn_mov_dpp(xb, 0x121, 0xf, 0xf, true), t2 = __builtin_amdgcn_mov_dpp(xb, 0x122, 0xf, 0xf, true);
;                         const h2 p1 = __builtin_bit_cast(h2, (fr == 0) ? t1p[n][q] : t1), p2 = __builtin_bit_cast(h2, (fr < 2) ? t2p[n][q] : t2), x2 = __builtin_bit_cast(h2, xb);
;                         t1p[n][q] = t1; t2p[n][q] = t2;
;                         const h2 c = p2 * w0h[n][q] + (p1 * w1h[n][q] + (x2 * w2h[n][q] + bbh[n][q]));
;                         const h2 ea = c * (h2){(_Float16)(-LOG2E), (_Float16)(-LOG2E)};
;                         h2 ex; ex.x = __builtin_exp2f16(ea.x); ex.y = __builtin_exp2f16(ea.y);
;                         const h2 dn = ex + (h2){(_Float16)1.f, (_Float16)1.f};
	v_exp_f16_sdwa v78, v78 dst_sel:WORD_0 dst_unused:UNUSED_PRESERVE src0_sel:WORD_0
	v_mov_b32_dpp v71, v70 row_ror:1 row_mask:0xf bank_mask:0xf bound_ctrl:1
	v_cndmask_b32_e64 v71, v71, v97, s[68:69]
	v_pk_add_f16 v78, v78, 1.0 op_sel_hi:[1,0]
	v_pk_mul_f16 v79, v89, v80
	v_rcp_f16_e32 v80, v78
	s_nop 0
	v_rcp_f16_sdwa v80, v78 dst_sel:WORD_1 dst_unused:UNUSED_PRESERVE src0_sel:WORD_1
	v_pk_mul_f32 v[72:73], v[72:73], v[88:89] op_sel_hi:[1,0]
	v_cvt_f32_f16_e32 v78, v79
	v_cvt_pkrtz_f16_f32 v72, v72, v73
	v_mov_b32_dpp v81, v70 row_ror:2 row_mask:0xf bank_mask:0xf bound_ctrl:1
	v_pk_fma_f16 v70, v135, v70, v138
	v_cndmask_b32_e64 v81, v81, v104, s[76:77]
	v_pk_fma_f16 v70, v134, v71, v70
	v_pk_mul_f16 v80, v82, v80
	v_pk_fma_f16 v81, v146, v81, v70
	v_mov_b32_dpp v73, v72 row_ror:1 row_mask:0xf bank_mask:0xf bound_ctrl:1
	v_pk_mul_f16 v70, v81, s52 op_sel_hi:[1,0]
	v_cvt_f32_f16_sdwa v71, v80 dst_sel:DWORD dst_unused:UNUSED_PAD src0_sel:WORD_1
	v_exp_f16_e32 v82, v70
	v_exp_f16_sdwa v83, v70 dst_sel:DWORD dst_unused:UNUSED_PAD src0_sel:WORD_1
	v_cvt_f32_f16_e32 v70, v80
	v_cndmask_b32_e64 v73, v73, v107, s[68:69]
	v_cvt_f32_f16_sdwa v79, v79 dst_sel:DWORD dst_unused:UNUSED_PAD src0_sel:WORD_1
	v_pack_b32_f16 v80, v82, v83
	v_mov_b32_dpp v83, v72 row_ror:2 row_mask:0xf bank_mask:0xf bound_ctrl:1
	v_pk_fma_f16 v72, v132, v72, v133
	v_cndmask_b32_e64 v83, v83, v110, s[76:77]
	v_pk_fma_f16 v72, v131, v73, v72
	v_pk_mul_f32 v[74:75], v[74:75], v[88:89] op_sel_hi:[1,0]
	v_pk_fma_f16 v83, v130, v83, v72
	v_pk_add_f16 v80, v80, 1.0 op_sel_hi:[1,0]
	v_pk_mul_f16 v72, v83, s52 op_sel_hi:[1,0]
	v_rcp_f16_e32 v82, v80
	v_exp_f16_e32 v84, v72
	v_exp_f16_sdwa v85, v72 dst_sel:DWORD dst_unused:UNUSED_PAD src0_sel:WORD_1
	v_rcp_f16_sdwa v80, v80 dst_sel:DWORD dst_unused:UNUSED_PAD src0_sel:WORD_1
	v_pk_mul_f32 v[72:73], v[74:75], v[78:79]
	v_pk_mul_f32 v[76:77], v[76:77], v[88:89] op_sel_hi:[1,0]
	v_pack_b32_f16 v75, v84, v85
	v_pk_add_f16 v75, v75, 1.0 op_sel_hi:[1,0]
	v_pk_mul_f32 v[70:71], v[76:77], v[70:71]
	v_rcp_f16_e32 v76, v75
	s_nop 0
	v_rcp_f16_sdwa v76, v75 dst_sel:WORD_1 dst_unused:UNUSED_PRESERVE src0_sel:WORD_1
	v_pack_b32_f16 v74, v82, v80
	v_pk_mul_f16 v75, v81, v74
	v_pk_mul_f32 v[66:67], v[66:67], v[88:89] op_sel_hi:[1,0]
	v_pk_mul_f16 v77, v83, v76
	v_pk_mul_f32 v[68:69], v[68:69], v[88:89] op_sel_hi:[1,0]
	v_fma_mix_f32 v74, v75, v66, 0 op_sel_hi:[1,0,0]
	v_fma_mix_f32 v75, v75, v67, 0 op_sel:[1,0,0] op_sel_hi:[1,0,0]
	v_cvt_pk_bf16_f32 v66, v72, v73
	v_cvt_pk_bf16_f32 v67, v70, v71
	ds_read_b128 v[70:73], v220
	v_fma_mix_f32 v76, v77, v68, 0 op_sel_hi:[1,0,0]
	v_fma_mix_f32 v77, v77, v69, 0 op_sel:[1,0,0] op_sel_hi:[1,0,0]
	v_cvt_pk_bf16_f32 v68, v74, v75
	v_or_b32_e32 v74, 48, v224
	v_mad_i64_i32 v[74:75], s[18:19], v74, s38, v[98:99]
	v_cvt_pk_bf16_f32 v69, v76, v77
	v_lshl_add_u64 v[74:75], v[74:75], 0, v[100:101]
	global_store_dwordx4 v[74:75], v[66:69], off
	ds_read_b128 v[66:69], v220 offset:16
	s_waitcnt lgkmcnt(1)
	v_cvt_pkrtz_f16_f32 v70, v70, v71
	v_mov_b32_dpp v74, v62 row_ror:1 row_mask:0xf bank_mask:0xf bound_ctrl:1
	v_mov_b32_dpp v75, v62 row_ror:2 row_mask:0xf bank_mask:0xf bound_ctrl:1
	v_mov_b32_dpp v71, v70 row_ror:1 row_mask:0xf bank_mask:0xf bound_ctrl:1
	v_mov_b32_dpp v70, v70 row_ror:2 row_mask:0xf bank_mask:0xf bound_ctrl:1
	v_cndmask_b32_e64 v63, v74, v71, s[68:69]
	v_pk_fma_f16 v62, v154, v62, v155
	v_cndmask_b32_e64 v70, v75, v70, s[76:77]
	v_pk_fma_f16 v62, v151, v63, v62
	v_cvt_pkrtz_f16_f32 v72, v72, v73
	v_pk_fma_f16 v70, v225, v70, v62
	s_waitcnt lgkmcnt(0)
	v_cvt_pkrtz_f16_f32 v66, v66, v67
	v_pk_mul_f16 v62, v70, s52 op_sel_hi:[1,0]
	v_mov_b32_dpp v73, v72 row_ror:1 row_mask:0xf bank_mask:0xf bound_ctrl:1
	v_exp_f16_e32 v71, v62
	v_exp_f16_sdwa v76, v62 dst_sel:DWORD dst_unused:UNUSED_PAD src0_sel:WORD_1
	v_pk_mul_f32 v[62:63], v[64:65], v[198:199] op_sel_hi:[1,0]
	v_mov_b32_dpp v72, v72 row_ror:2 row_mask:0xf bank_mask:0xf bound_ctrl:1
	v_cvt_pkrtz_f16_f32 v62, v62, v63
	v_pack_b32_f16 v64, v71, v76
	v_pk_add_f16 v64, v64, 1.0 op_sel_hi:[1,0]
	v_mov_b32_dpp v71, v62 row_ror:1 row_mask:0xf bank_mask:0xf bound_ctrl:1
	v_mov_b32_dpp v76, v62 row_ror:2 row_mask:0xf bank_mask:0xf bound_ctrl:1
	v_cndmask_b32_e64 v63, v71, v73, s[68:69]
	v_pk_fma_f16 v62, v149, v62, v150
	v_cndmask_b32_e64 v72, v76, v72, s[76:77]
	v_pk_fma_f16 v62, v148, v63, v62
	v_rcp_f16_sdwa v64, v64 dst_sel:WORD_1 dst_unused:UNUSED_PRESERVE src0_sel:WORD_1
	v_pk_fma_f16 v72, v147, v72, v62
	v_rcp_f16_sdwa v64, v64 dst_sel:WORD_0 dst_unused:UNUSED_PRESERVE src0_sel:WORD_0
	v_pk_mul_f16 v62, v72, s52 op_sel_hi:[1,0]
	v_mov_b32_dpp v67, v66 row_ror:1 row_mask:0xf bank_mask:0xf bound_ctrl:1
	v_exp_f16_sdwa v62, v62 dst_sel:WORD_1 dst_unused:UNUSED_PRESERVE src0_sel:WORD_1
	s_nop 0
	v_exp_f16_sdwa v62, v62 dst_sel:WORD_0 dst_unused:UNUSED_PRESERVE src0_sel:WORD_0
	v_mov_b32_dpp v66, v66 row_ror:2 row_mask:0xf bank_mask:0xf bound_ctrl:1
	v_cvt_pkrtz_f16_f32 v68, v68, v69
	v_pk_add_f16 v62, v62, 1.0 op_sel_hi:[1,0]
	v_pk_mul_f16 v63, v70, v64
	v_rcp_f16_e32 v64, v62
	s_nop 0
	v_rcp_f16_sdwa v64, v62 dst_sel:WORD_1 dst_unused:UNUSED_PRESERVE src0_sel:WORD_1
	v_mov_b32_dpp v70, v54 row_ror:2 row_mask:0xf bank_mask:0xf bound_ctrl:1
	v_cndmask_b32_e64 v66, v70, v66, s[76:77]
	v_mov_b32_dpp v69, v68 row_ror:1 row_mask:0xf bank_mask:0xf bound_ctrl:1
	v_mov_b32_dpp v65, v54 row_ror:1 row_mask:0xf bank_mask:0xf bound_ctrl:1
	v_cndmask_b32_e64 v55, v65, v67, s[68:69]
	v_pk_fma_f16 v54, v135, v54, v138
	v_pk_mul_f16 v64, v72, v64
	v_pk_fma_f16 v54, v134, v55, v54
	v_cvt_f32_f16_sdwa v55, v64 dst_sel:DWORD dst_unused:UNUSED_PAD src0_sel:WORD_1
; __device__ __forceinline__ unsigned cvt_pk_bf16(float lo, float hi) { const f32x2 v = {lo, hi}; const bf16x2_t b = __builtin_convertvector(v, bf16x2_t); return __builtin_bit_cast(unsigned, b); }
;     __device__ __forceinline__ void operator()(const f32x4 (&acc)[2][2][4][2], const pg8::Unit& u, int ui, int wr, int wc, int fr, int fq) const {
;     ...
;             for (int m = 0; m < 4; ++m) {
;                 const int rl = ai * 128 + wr * 64 + m * 16 + fr;
;                 f32x4 a[2], o[2];
; #pragma unroll
;                 for (int n = 0; n < 2; ++n) {
;                     a[n] = acc[ai][0][m][n] * rr[ai][m];
;                     const f32x4 v = acc[ai][1][m][n] * rr[ai][m];
; #pragma unroll
;                     for (int q = 0; q < 2; ++q) {
;                         const int xb = __builtin_bit_cast(int, __builtin_amdgcn_cvt_pkrtz(a[n][2 * q], a[n][2 * q + 1]));
;                         const int t1 = __builtin_amdgcn_mov_dpp(xb, 0x121, 0xf, 0xf, true), t2 = __builtin_amdgcn_mov_dpp(xb, 0x122, 0xf, 0xf, true);
;                         const h2 p1 = __builtin_bit_cast(h2, (fr == 0) ? t1p[n][q] : t1), p2 = __builtin_bit_cast(h2, (fr < 2) ? t2p[n][q] : t2), x2 = __builtin_bit_cast(h2, xb);
;                         t1p[n][q] = t1; t2p[n][q] = t2;
;                         const h2 c = p2 * w0h[n][q] + (p1 * w1h[n][q] + (x2 * w2h[n][q] + bbh[n][q]));
;                         const h2 ea = c * (h2){(_Float16)(-LOG2E), (_Float16)(-LOG2E)};
;                         h2 ex; ex.x = __builtin_exp2f16(ea.x); ex.y = __builtin_exp2f16(ea.y);
;                         const h2 dn = ex + (h2){(_Float16)1.f, (_Float16)1.f};
;                         h2 rc; rc.x = __builtin_amdgcn_rcph(dn.x); rc.y = __builtin_amdgcn_rcph(dn.y);
;                         const h2 sg = c * rc;
;                         o[n][2 * q] = (float)sg.x * v[2 * q]; o[n][2 * q + 1] = (float)sg.y * v[2 * q + 1];
;                     }
;                 }
;                 u32x4 pk; pk.x = cvt_pk_bf16(o[0][0], o[0][1]); pk.y = cvt_pk_bf16(o[0][2], o[0][3]); pk.z = cvt_pk_bf16(o[1][0], o[1][1]); pk.w = cvt_pk_bf16(o[1][2], o[1][3]);
;                 *(u32x4*)(U + (size_t)(u.pm * 256 + rl) * FF + fcol) = pk;
	v_pk_fma_f16 v66, v146, v66, v54
	v_mov_b32_dpp v68, v68 row_ror:2 row_mask:0xf bank_mask:0xf bound_ctrl:1
	v_pk_mul_f16 v54, v66, s52 op_sel_hi:[1,0]
	v_mov_b32_dpp v73, v56 row_ror:2 row_mask:0xf bank_mask:0xf bound_ctrl:1
	v_exp_f16_e32 v67, v54
	v_exp_f16_sdwa v72, v54 dst_sel:DWORD dst_unused:UNUSED_PAD src0_sel:WORD_1
	v_cvt_f32_f16_e32 v54, v64
	v_cndmask_b32_e64 v68, v73, v68, s[76:77]
	v_pack_b32_f16 v64, v67, v72
	v_mov_b32_dpp v72, v56 row_ror:1 row_mask:0xf bank_mask:0xf bound_ctrl:1
	v_cndmask_b32_e64 v57, v72, v69, s[68:69]
	v_pk_fma_f16 v56, v132, v56, v133
	v_pk_fma_f16 v56, v131, v57, v56
	v_pk_add_f16 v64, v64, 1.0 op_sel_hi:[1,0]
	v_pk_fma_f16 v68, v130, v68, v56
	v_rcp_f16_e32 v67, v64
	v_pk_mul_f16 v56, v68, s52 op_sel_hi:[1,0]
	v_rcp_f16_sdwa v64, v64 dst_sel:DWORD dst_unused:UNUSED_PAD src0_sel:WORD_1
	v_exp_f16_e32 v69, v56
	v_exp_f16_sdwa v78, v56 dst_sel:DWORD dst_unused:UNUSED_PAD src0_sel:WORD_1
	v_fma_mix_f32 v56, v63, v58, 0 op_sel_hi:[1,0,0]
	v_fma_mix_f32 v57, v63, v59, 0 op_sel:[1,0,0] op_sel_hi:[1,0,0]
	v_pk_mul_f32 v[54:55], v[60:61], v[54:55]
	v_pack_b32_f16 v58, v67, v64
	v_pack_b32_f16 v59, v69, v78
	v_pk_add_f16 v59, v59, 1.0 op_sel_hi:[1,0]
	v_add_u32_e32 v77, 0x80, v224
	v_rcp_f16_e32 v60, v59
	s_nop 0
	v_rcp_f16_sdwa v60, v59 dst_sel:WORD_1 dst_unused:UNUSED_PRESERVE src0_sel:WORD_1
	v_pk_mul_f16 v59, v66, v58
	v_pk_mul_f32 v[30:31], v[30:31], v[196:197] op_sel_hi:[1,0]
	v_pk_mul_f16 v61, v68, v60
	v_cvt_pkrtz_f16_f32 v30, v30, v31
	v_fma_mix_f32 v58, v59, v50, 0 op_sel_hi:[1,0,0]
	v_fma_mix_f32 v59, v59, v51, 0 op_sel:[1,0,0] op_sel_hi:[1,0,0]
	v_cvt_pk_bf16_f32 v50, v56, v57
	v_mov_b32_e32 v56, v199
	v_pk_mul_f32 v[46:47], v[46:47], v[56:57] op_sel_hi:[1,0]
	v_fma_mix_f32 v60, v61, v52, 0 op_sel_hi:[1,0,0]
	v_fma_mix_f32 v61, v61, v53, 0 op_sel:[1,0,0] op_sel_hi:[1,0,0]
	v_cvt_pkrtz_f16_f32 v46, v46, v47
	v_cvt_pk_bf16_f32 v52, v58, v59
	v_cvt_pk_bf16_f32 v51, v54, v55
	v_mov_b32_dpp v57, v46 row_ror:1 row_mask:0xf bank_mask:0xf bound_ctrl:1
	v_mov_b32_dpp v58, v46 row_ror:2 row_mask:0xf bank_mask:0xf bound_ctrl:1
	v_cndmask_b32_e64 v47, v57, v74, s[68:69]
	v_pk_fma_f16 v46, v154, v46, v155
	v_cndmask_b32_e64 v59, v58, v75, s[76:77]
	v_pk_fma_f16 v46, v151, v47, v46
	v_mad_i64_i32 v[54:55], s[18:19], v77, s38, v[98:99]
	v_pk_fma_f16 v59, v225, v59, v46
	v_cvt_pk_bf16_f32 v53, v60, v61
	v_pk_mul_f16 v46, v59, s52 op_sel_hi:[1,0]
	v_pk_mul_f32 v[38:39], v[38:39], v[56:57] op_sel_hi:[1,0]
	v_exp_f16_e32 v60, v46
	v_exp_f16_sdwa v61, v46 dst_sel:DWORD dst_unused:UNUSED_PAD src0_sel:WORD_1
	v_lshl_add_u64 v[46:47], v[54:55], 0, v[100:101]
	global_store_dwordx4 v[46:47], v[50:53], off
	v_pk_mul_f32 v[46:47], v[48:49], v[56:57] op_sel_hi:[1,0]
	v_pack_b32_f16 v48, v60, v61
	v_cvt_pkrtz_f16_f32 v46, v46, v47
	v_pk_add_f16 v48, v48, 1.0 op_sel_hi:[1,0]
	v_cvt_pkrtz_f16_f32 v38, v38, v39
	v_mov_b32_dpp v50, v46 row_ror:1 row_mask:0xf bank_mask:0xf bound_ctrl:1
	v_mov_b32_dpp v51, v46 row_ror:2 row_mask:0xf bank_mask:0xf bound_ctrl:1
	v_cndmask_b32_e64 v47, v50, v71, s[68:69]
	v_pk_fma_f16 v46, v149, v46, v150
	v_cndmask_b32_e64 v52, v51, v76, s[76:77]
	v_pk_fma_f16 v46, v148, v47, v46
	v_rcp_f16_sdwa v48, v48 dst_sel:WORD_1 dst_unused:UNUSED_PRESERVE src0_sel:WORD_1
	v_pk_fma_f16 v52, v147, v52, v46
	v_rcp_f16_sdwa v48, v48 dst_sel:WORD_0 dst_unused:UNUSED_PRESERVE src0_sel:WORD_0
	v_pk_mul_f16 v46, v52, s52 op_sel_hi:[1,0]
	v_pk_mul_f32 v[40:41], v[40:41], v[56:57] op_sel_hi:[1,0]
	v_exp_f16_sdwa v46, v46 dst_sel:WORD_1 dst_unused:UNUSED_PRESERVE src0_sel:WORD_1
	s_nop 0
	v_exp_f16_sdwa v46, v46 dst_sel:WORD_0 dst_unused:UNUSED_PRESERVE src0_sel:WORD_0
	v_cvt_pkrtz_f16_f32 v40, v40, v41
	v_pk_mul_f32 v[42:43], v[42:43], v[56:57] op_sel_hi:[1,0]
	v_pk_add_f16 v46, v46, 1.0 op_sel_hi:[1,0]
	v_pk_mul_f16 v47, v59, v48
	v_rcp_f16_e32 v48, v46
	s_nop 0
	v_rcp_f16_sdwa v48, v46 dst_sel:WORD_1 dst_unused:UNUSED_PRESERVE src0_sel:WORD_1
	v_mov_b32_dpp v59, v40 row_ror:2 row_mask:0xf bank_mask:0xf bound_ctrl:1
	v_cndmask_b32_e64 v60, v59, v73, s[76:77]
	v_cvt_f32_f16_e32 v46, v47
	v_mov_b32_dpp v49, v38 row_ror:1 row_mask:0xf bank_mask:0xf bound_ctrl:1
	v_pk_mul_f16 v48, v52, v48
	v_mov_b32_dpp v52, v38 row_ror:2 row_mask:0xf bank_mask:0xf bound_ctrl:1
	v_cndmask_b32_e64 v39, v49, v65, s[68:69]
	v_pk_fma_f16 v38, v135, v38, v138
	v_cndmask_b32_e64 v53, v52, v70, s[76:77]
	v_pk_fma_f16 v38, v134, v39, v38
	v_cvt_f32_f16_sdwa v39, v48 dst_sel:DWORD dst_unused:UNUSED_PAD src0_sel:WORD_1
	v_pk_fma_f16 v53, v146, v53, v38
	v_cvt_f32_f16_sdwa v47, v47 dst_sel:DWORD dst_unused:UNUSED_PAD src0_sel:WORD_1
	v_pk_mul_f16 v38, v53, s52 op_sel_hi:[1,0]
	v_pk_mul_f32 v[44:45], v[44:45], v[56:57] op_sel_hi:[1,0]
	v_exp_f16_e32 v54, v38
	v_exp_f16_sdwa v55, v38 dst_sel:DWORD dst_unused:UNUSED_PAD src0_sel:WORD_1
	v_cvt_f32_f16_e32 v38, v48
	v_pk_mul_f32 v[34:35], v[34:35], v[56:57] op_sel_hi:[1,0]
	v_pk_mul_f32 v[36:37], v[36:37], v[56:57] op_sel_hi:[1,0]
	v_pack_b32_f16 v48, v54, v55
	v_mov_b32_dpp v55, v40 row_ror:1 row_mask:0xf bank_mask:0xf bound_ctrl:1
	v_cndmask_b32_e64 v41, v55, v72, s[68:69]
	v_pk_fma_f16 v40, v132, v40, v133
	v_pk_add_f16 v48, v48, 1.0 op_sel_hi:[1,0]
	v_pk_fma_f16 v40, v131, v41, v40
	v_rcp_f16_e32 v54, v48
	v_pk_fma_f16 v60, v130, v60, v40
	v_rcp_f16_sdwa v48, v48 dst_sel:DWORD dst_unused:UNUSED_PAD src0_sel:WORD_1
	v_pk_mul_f16 v40, v60, s52 op_sel_hi:[1,0]
	v_pk_mul_f32 v[38:39], v[44:45], v[38:39]
	v_exp_f16_e32 v61, v40
	v_exp_f16_sdwa v62, v40 dst_sel:DWORD dst_unused:UNUSED_PAD src0_sel:WORD_1
	v_pk_mul_f32 v[40:41], v[42:43], v[46:47]
	v_pack_b32_f16 v42, v54, v48
; __device__ __forceinline__ unsigned cvt_pk_bf16(float lo, float hi) { const f32x2 v = {lo, hi}; const bf16x2_t b = __builtin_convertvector(v, bf16x2_t); return __builtin_bit_cast(unsigned, b); }
;     __device__ __forceinline__ void operator()(const f32x4 (&acc)[2][2][4][2], const pg8::Unit& u, int ui, int wr, int wc, int fr, int fq) const {
;     ...
;             for (int m = 0; m < 4; ++m) {
;                 const int rl = ai * 128 + wr * 64 + m * 16 + fr;
;                 f32x4 a[2], o[2];
; #pragma unroll
;                 for (int n = 0; n < 2; ++n) {
;                     a[n] = acc[ai][0][m][n] * rr[ai][m];
;                     const f32x4 v = acc[ai][1][m][n] * rr[ai][m];
; #pragma unroll
;                     for (int q = 0; q < 2; ++q) {
;                         const int xb = __builtin_bit_cast(int, __builtin_amdgcn_cvt_pkrtz(a[n][2 * q], a[n][2 * q + 1]));
;                         const int t1 = __builtin_amdgcn_mov_dpp(xb, 0x121, 0xf, 0xf, true), t2 = __builtin_amdgcn_mov_dpp(xb, 0x122, 0xf, 0xf, true);
;                         const h2 p1 = __builtin_bit_cast(h2, (fr == 0) ? t1p[n][q] : t1), p2 = __builtin_bit_cast(h2, (fr < 2) ? t2p[n][q] : t2), x2 = __builtin_bit_cast(h2, xb);
;                         t1p[n][q] = t1; t2p[n][q] = t2;
;                         const h2 c = p2 * w0h[n][q] + (p1 * w1h[n][q] + (x2 * w2h[n][q] + bbh[n][q]));
;                         const h2 ea = c * (h2){(_Float16)(-LOG2E), (_Float16)(-LOG2E)};
;                         h2 ex; ex.x = __builtin_exp2f16(ea.x); ex.y = __builtin_exp2f16(ea.y);
;                         const h2 dn = ex + (h2){(_Float16)1.f, (_Float16)1.f};
;                         h2 rc; rc.x = __builtin_amdgcn_rcph(dn.x); rc.y = __builtin_amdgcn_rcph(dn.y);
;                         const h2 sg = c * rc;
;                         o[n][2 * q] = (float)sg.x * v[2 * q]; o[n][2 * q + 1] = (float)sg.y * v[2 * q + 1];
;                     }
;                 }
;                 u32x4 pk; pk.x = cvt_pk_bf16(o[0][0], o[0][1]); pk.y = cvt_pk_bf16(o[0][2], o[0][3]); pk.z = cvt_pk_bf16(o[1][0], o[1][1]); pk.w = cvt_pk_bf16(o[1][2], o[1][3]);
;                 *(u32x4*)(U + (size_t)(u.pm * 256 + rl) * FF + fcol) = pk;
	v_pk_mul_f32 v[22:23], v[22:23], v[196:197] op_sel_hi:[1,0]
	v_pack_b32_f16 v43, v61, v62
	v_pk_add_f16 v43, v43, 1.0 op_sel_hi:[1,0]
	v_cvt_pkrtz_f16_f32 v22, v22, v23
	v_rcp_f16_e32 v44, v43
	s_nop 0
	v_rcp_f16_sdwa v44, v43 dst_sel:WORD_1 dst_unused:UNUSED_PRESERVE src0_sel:WORD_1
	v_pk_mul_f16 v43, v53, v42
	v_pk_mul_f32 v[24:25], v[24:25], v[196:197] op_sel_hi:[1,0]
	v_pk_mul_f16 v45, v60, v44
	v_cvt_pkrtz_f16_f32 v24, v24, v25
	v_fma_mix_f32 v42, v43, v34, 0 op_sel_hi:[1,0,0]
	v_fma_mix_f32 v43, v43, v35, 0 op_sel:[1,0,0] op_sel_hi:[1,0,0]
	v_cvt_pk_bf16_f32 v34, v40, v41
	v_mov_b32_dpp v40, v30 row_ror:1 row_mask:0xf bank_mask:0xf bound_ctrl:1
	v_mov_b32_dpp v41, v30 row_ror:2 row_mask:0xf bank_mask:0xf bound_ctrl:1
	v_cndmask_b32_e64 v31, v40, v57, s[68:69]
	v_pk_fma_f16 v30, v154, v30, v155
	v_fma_mix_f32 v44, v45, v36, 0 op_sel_hi:[1,0,0]
	v_fma_mix_f32 v45, v45, v37, 0 op_sel:[1,0,0] op_sel_hi:[1,0,0]
	v_cvt_pk_bf16_f32 v36, v42, v43
	v_cndmask_b32_e64 v42, v41, v58, s[76:77]
	v_pk_fma_f16 v30, v151, v31, v30
	v_cvt_pk_bf16_f32 v35, v38, v39
	v_add_u32_e32 v38, 0x90, v224
	v_pk_fma_f16 v42, v225, v42, v30
	v_mad_i64_i32 v[38:39], s[18:19], v38, s38, v[98:99]
	v_pk_mul_f16 v30, v42, s52 op_sel_hi:[1,0]
	v_cvt_pk_bf16_f32 v37, v44, v45
	v_exp_f16_e32 v43, v30
	v_exp_f16_sdwa v44, v30 dst_sel:DWORD dst_unused:UNUSED_PAD src0_sel:WORD_1
	v_lshl_add_u64 v[30:31], v[38:39], 0, v[100:101]
	global_store_dwordx4 v[30:31], v[34:37], off
	v_pk_mul_f32 v[30:31], v[32:33], v[196:197] op_sel_hi:[1,0]
	v_pack_b32_f16 v32, v43, v44
	v_cvt_pkrtz_f16_f32 v30, v30, v31
	v_pk_add_f16 v32, v32, 1.0 op_sel_hi:[1,0]
	v_pk_mul_f32 v[26:27], v[26:27], v[196:197] op_sel_hi:[1,0]
	v_mov_b32_dpp v34, v30 row_ror:1 row_mask:0xf bank_mask:0xf bound_ctrl:1
	v_mov_b32_dpp v35, v30 row_ror:2 row_mask:0xf bank_mask:0xf bound_ctrl:1
	v_cndmask_b32_e64 v31, v34, v50, s[68:69]
	v_pk_fma_f16 v30, v149, v30, v150
	v_cndmask_b32_e64 v36, v35, v51, s[76:77]
	v_pk_fma_f16 v30, v148, v31, v30
	v_rcp_f16_sdwa v32, v32 dst_sel:WORD_1 dst_unused:UNUSED_PRESERVE src0_sel:WORD_1
	v_pk_fma_f16 v36, v147, v36, v30
	v_rcp_f16_sdwa v32, v32 dst_sel:WORD_0 dst_unused:UNUSED_PRESERVE src0_sel:WORD_0
	v_pk_mul_f16 v30, v36, s52 op_sel_hi:[1,0]
	v_pk_mul_f32 v[28:29], v[28:29], v[196:197] op_sel_hi:[1,0]
	v_exp_f16_sdwa v30, v30 dst_sel:WORD_1 dst_unused:UNUSED_PRESERVE src0_sel:WORD_1
	s_nop 0
	v_exp_f16_sdwa v30, v30 dst_sel:WORD_0 dst_unused:UNUSED_PRESERVE src0_sel:WORD_0
	v_pk_mul_f32 v[18:19], v[18:19], v[196:197] op_sel_hi:[1,0]
	v_pk_mul_f32 v[20:21], v[20:21], v[196:197] op_sel_hi:[1,0]
	v_pk_add_f16 v30, v30, 1.0 op_sel_hi:[1,0]
	v_pk_mul_f16 v31, v42, v32
	v_rcp_f16_e32 v32, v30
	s_nop 0
	v_rcp_f16_sdwa v32, v30 dst_sel:WORD_1 dst_unused:UNUSED_PRESERVE src0_sel:WORD_1
	v_mov_b32_dpp v42, v24 row_ror:2 row_mask:0xf bank_mask:0xf bound_ctrl:1
	v_cndmask_b32_e64 v43, v42, v59, s[76:77]
	v_cvt_f32_f16_e32 v30, v31
	v_mov_b32_dpp v33, v22 row_ror:1 row_mask:0xf bank_mask:0xf bound_ctrl:1
	v_pk_mul_f16 v32, v36, v32
	v_mov_b32_dpp v36, v22 row_ror:2 row_mask:0xf bank_mask:0xf bound_ctrl:1
	v_cndmask_b32_e64 v23, v33, v49, s[68:69]
	v_pk_fma_f16 v22, v135, v22, v138
	v_cndmask_b32_e64 v37, v36, v52, s[76:77]
	v_pk_fma_f16 v22, v134, v23, v22
	v_cvt_f32_f16_sdwa v23, v32 dst_sel:DWORD dst_unused:UNUSED_PAD src0_sel:WORD_1
	v_pk_fma_f16 v37, v146, v37, v22
	v_cvt_f32_f16_sdwa v31, v31 dst_sel:DWORD dst_unused:UNUSED_PAD src0_sel:WORD_1
	v_pk_mul_f16 v22, v37, s52 op_sel_hi:[1,0]
	s_nop 0
	v_exp_f16_e32 v38, v22
	v_exp_f16_sdwa v39, v22 dst_sel:DWORD dst_unused:UNUSED_PAD src0_sel:WORD_1
	v_cvt_f32_f16_e32 v22, v32
	v_pack_b32_f16 v32, v38, v39
	v_mov_b32_dpp v39, v24 row_ror:1 row_mask:0xf bank_mask:0xf bound_ctrl:1
	v_cndmask_b32_e64 v25, v39, v55, s[68:69]
	v_pk_fma_f16 v24, v132, v24, v133
	v_pk_add_f16 v32, v32, 1.0 op_sel_hi:[1,0]
	v_pk_fma_f16 v24, v131, v25, v24
	v_rcp_f16_e32 v38, v32
	v_pk_fma_f16 v43, v130, v43, v24
	v_rcp_f16_sdwa v32, v32 dst_sel:DWORD dst_unused:UNUSED_PAD src0_sel:WORD_1
	v_pk_mul_f16 v24, v43, s52 op_sel_hi:[1,0]
	v_pk_mul_f32 v[22:23], v[28:29], v[22:23]
	v_exp_f16_e32 v44, v24
	v_exp_f16_sdwa v45, v24 dst_sel:DWORD dst_unused:UNUSED_PAD src0_sel:WORD_1
	v_pk_mul_f32 v[24:25], v[26:27], v[30:31]
	v_pack_b32_f16 v26, v38, v32
	v_pack_b32_f16 v27, v44, v45
	v_pk_add_f16 v27, v27, 1.0 op_sel_hi:[1,0]
	s_nop 0
	v_rcp_f16_e32 v28, v27
	s_nop 0
	v_rcp_f16_sdwa v28, v27 dst_sel:WORD_1 dst_unused:UNUSED_PRESERVE src0_sel:WORD_1
	v_pk_mul_f16 v27, v37, v26
	v_pk_mul_f16 v29, v43, v28
	v_fma_mix_f32 v26, v27, v18, 0 op_sel_hi:[1,0,0]
	v_fma_mix_f32 v27, v27, v19, 0 op_sel:[1,0,0] op_sel_hi:[1,0,0]
	v_cvt_pk_bf16_f32 v18, v24, v25
	v_mov_b32_e32 v24, v197
	v_pk_mul_f32 v[14:15], v[14:15], v[24:25] op_sel_hi:[1,0]
	v_fma_mix_f32 v28, v29, v20, 0 op_sel_hi:[1,0,0]
;     __device__ __forceinline__ void operator()(const f32x4 (&acc)[2][2][4][2], const pg8::Unit& u, int ui, int wr, int wc, int fr, int fq) const {
;     ...
;             for (int m = 0; m < 4; ++m) {
;                 const int rl = ai * 128 + wr * 64 + m * 16 + fr;
;                 f32x4 a[2], o[2];
; #pragma unroll
;                 for (int n = 0; n < 2; ++n) {
;                     a[n] = acc[ai][0][m][n] * rr[ai][m];
;                     const f32x4 v = acc[ai][1][m][n] * rr[ai][m];
; #pragma unroll
;                     for (int q = 0; q < 2; ++q) {
;                         const int xb = __builtin_bit_cast(int, __builtin_amdgcn_cvt_pkrtz(a[n][2 * q], a[n][2 * q + 1]));
;                         const int t1 = __builtin_amdgcn_mov_dpp(xb, 0x121, 0xf, 0xf, true), t2 = __builtin_amdgcn_mov_dpp(xb, 0x122, 0xf, 0xf, true);
;                         const h2 p1 = __builtin_bit_cast(h2, (fr == 0) ? t1p[n][q] : t1), p2 = __builtin_bit_cast(h2, (fr < 2) ? t2p[n][q] : t2), x2 = __builtin_bit_cast(h2, xb);
;                         t1p[n][q] = t1; t2p[n][q] = t2;
;                         const h2 c = p2 * w0h[n][q] + (p1 * w1h[n][q] + (x2 * w2h[n][q] + bbh[n][q]));
;                         const h2 ea = c * (h2){(_Float16)(-LOG2E), (_Float16)(-LOG2E)};
;                         h2 ex; ex.x = __builtin_exp2f16(ea.x); ex.y = __builtin_exp2f16(ea.y);
;                         const h2 dn = ex + (h2){(_Float16)1.f, (_Float16)1.f};
;                         h2 rc; rc.x = __builtin_amdgcn_rcph(dn.x); rc.y = __builtin_amdgcn_rcph(dn.y);
;                         const h2 sg = c * rc;
;                         o[n][2 * q] = (float)sg.x * v[2 * q]; o[n][2 * q + 1] = (float)sg.y * v[2 * q + 1];
;                     }
;                 }
;                 u32x4 pk; pk.x = cvt_pk_bf16(o[0][0], o[0][1]); pk.y = cvt_pk_bf16(o[0][2], o[0][3]); pk.z = cvt_pk_bf16(o[1][0], o[1][1]); pk.w = cvt_pk_bf16(o[1][2], o[1][3]);
;                 *(u32x4*)(U + (size_t)(u.pm * 256 + rl) * FF + fcol) = pk;
;                 if (ai == 0 && m == 0 && wr == 0 && fr < 2) {
; #pragma unroll
;                     for (int n = 0; n < 2; ++n) { *(f32x4*)(topa + (size_t)(u.pm * 2 + fr) * FF + fcol + 4 * n) = a[n]; *(f32x4*)(topv + (size_t)(u.pm * 2 + fr) * FF + fcol + 4 * n) = acc[0][1][0][n] * rr[0][0]; }
;                 }
;                 if (ai == 1 && m == 3 && wr == 1 && fr >= 14) {
	v_fma_mix_f32 v29, v29, v21, 0 op_sel:[1,0,0] op_sel_hi:[1,0,0]
	v_cvt_pkrtz_f16_f32 v25, v14, v15
	v_cvt_pk_bf16_f32 v20, v26, v27
	v_cvt_pk_bf16_f32 v19, v22, v23
	v_mov_b32_dpp v26, v25 row_ror:1 row_mask:0xf bank_mask:0xf bound_ctrl:1
	v_mov_b32_dpp v27, v25 row_ror:2 row_mask:0xf bank_mask:0xf bound_ctrl:1
	v_cndmask_b32_e64 v26, v26, v40, s[68:69]
	v_pk_fma_f16 v25, v154, v25, v155
	v_add_u32_e32 v22, 0xa0, v224
	v_cndmask_b32_e64 v27, v27, v41, s[76:77]
	v_pk_fma_f16 v25, v151, v26, v25
	v_mad_i64_i32 v[22:23], s[18:19], v22, s38, v[98:99]
	v_pk_fma_f16 v25, v225, v27, v25
	v_cvt_pk_bf16_f32 v21, v28, v29
	v_pk_mul_f16 v26, v25, s52 op_sel_hi:[1,0]
	v_lshl_add_u64 v[22:23], v[22:23], 0, v[100:101]
	v_pk_mul_f32 v[16:17], v[16:17], v[24:25] op_sel_hi:[1,0]
	v_exp_f16_e32 v27, v26
	v_exp_f16_sdwa v26, v26 dst_sel:DWORD dst_unused:UNUSED_PAD src0_sel:WORD_1
	global_store_dwordx4 v[22:23], v[18:21], off
	v_pk_mul_f32 v[6:7], v[6:7], v[24:25] op_sel_hi:[1,0]
	v_pk_mul_f32 v[12:13], v[12:13], v[24:25] op_sel_hi:[1,0]
	v_cvt_pkrtz_f16_f32 v20, v16, v17
	v_pack_b32_f16 v18, v27, v26
	v_pk_add_f16 v18, v18, 1.0 op_sel_hi:[1,0]
	v_mov_b32_dpp v21, v20 row_ror:1 row_mask:0xf bank_mask:0xf bound_ctrl:1
	v_mov_b32_dpp v22, v20 row_ror:2 row_mask:0xf bank_mask:0xf bound_ctrl:1
	v_cndmask_b32_e64 v21, v21, v34, s[68:69]
	v_pk_fma_f16 v20, v149, v20, v150
	v_cndmask_b32_e64 v22, v22, v35, s[76:77]
	v_pk_fma_f16 v20, v148, v21, v20
	v_rcp_f16_sdwa v18, v18 dst_sel:WORD_1 dst_unused:UNUSED_PRESERVE src0_sel:WORD_1
	v_pk_fma_f16 v20, v147, v22, v20
	v_rcp_f16_sdwa v18, v18 dst_sel:WORD_0 dst_unused:UNUSED_PRESERVE src0_sel:WORD_0
	v_pk_mul_f16 v21, v20, s52 op_sel_hi:[1,0]
	v_pk_mul_f32 v[10:11], v[10:11], v[24:25] op_sel_hi:[1,0]
	v_exp_f16_e32 v19, v21
	s_nop 0
	v_exp_f16_sdwa v19, v21 dst_sel:WORD_1 dst_unused:UNUSED_PRESERVE src0_sel:WORD_1
	s_nop 0
	v_pk_add_f16 v19, v19, 1.0 op_sel_hi:[1,0]
	s_nop 0
	v_rcp_f16_e32 v21, v19
	s_nop 0
	v_rcp_f16_sdwa v21, v19 dst_sel:WORD_1 dst_unused:UNUSED_PRESERVE src0_sel:WORD_1
	v_pk_mul_f16 v19, v25, v18
	v_pk_mul_f16 v21, v20, v21
	v_cvt_pkrtz_f16_f32 v20, v6, v7
	s_nop 1
	v_mov_b32_dpp v22, v20 row_ror:1 row_mask:0xf bank_mask:0xf bound_ctrl:1
	v_mov_b32_dpp v23, v20 row_ror:2 row_mask:0xf bank_mask:0xf bound_ctrl:1
	v_cndmask_b32_e64 v22, v22, v33, s[68:69]
	v_pk_fma_f16 v20, v135, v20, v138
	v_cndmask_b32_e64 v23, v23, v36, s[76:77]
	v_pk_fma_f16 v20, v134, v22, v20
	v_fma_mix_f32 v10, v19, v10, 0 op_sel_hi:[1,0,0]
	v_fma_mix_f32 v11, v19, v11, 0 op_sel:[1,0,0] op_sel_hi:[1,0,0]
	v_pk_fma_f16 v22, v146, v23, v20
	s_nop 0
	v_pk_mul_f16 v20, v22, s52 op_sel_hi:[1,0]
	s_nop 0
	v_exp_f16_sdwa v25, v20 dst_sel:DWORD dst_unused:UNUSED_PAD src0_sel:WORD_1
	v_exp_f16_e32 v23, v20
	v_pk_mul_f32 v[8:9], v[8:9], v[24:25] op_sel_hi:[1,0]
	v_pack_b32_f16 v23, v23, v25
	v_cvt_pkrtz_f16_f32 v26, v8, v9
	v_pk_add_f16 v23, v23, 1.0 op_sel_hi:[1,0]
	v_fma_mix_f32 v12, v21, v12, 0 op_sel_hi:[1,0,0]
	v_fma_mix_f32 v13, v21, v13, 0 op_sel:[1,0,0] op_sel_hi:[1,0,0]
	v_mov_b32_dpp v27, v26 row_ror:1 row_mask:0xf bank_mask:0xf bound_ctrl:1
	v_mov_b32_dpp v28, v26 row_ror:2 row_mask:0xf bank_mask:0xf bound_ctrl:1
	v_cndmask_b32_e64 v27, v27, v39, s[68:69]
	v_pk_fma_f16 v26, v132, v26, v133
	v_cndmask_b32_e64 v28, v28, v42, s[76:77]
	v_pk_fma_f16 v26, v131, v27, v26
	v_rcp_f16_e32 v25, v23
	v_pk_fma_f16 v26, v130, v28, v26
	v_rcp_f16_sdwa v23, v23 dst_sel:DWORD dst_unused:UNUSED_PAD src0_sel:WORD_1
	v_pk_mul_f16 v27, v26, s52 op_sel_hi:[1,0]
	v_pk_mul_f32 v[2:3], v[2:3], v[24:25] op_sel_hi:[1,0]
	v_exp_f16_e32 v19, v27
	s_nop 0
	v_exp_f16_sdwa v19, v27 dst_sel:WORD_1 dst_unused:UNUSED_PRESERVE src0_sel:WORD_1
	v_pack_b32_f16 v18, v25, v23
	v_pk_mul_f32 v[4:5], v[4:5], v[24:25] op_sel_hi:[1,0]
	v_pk_add_f16 v19, v19, 1.0 op_sel_hi:[1,0]
	s_nop 0
	v_rcp_f16_e32 v20, v19
	s_nop 0
	v_rcp_f16_sdwa v20, v19 dst_sel:WORD_1 dst_unused:UNUSED_PRESERVE src0_sel:WORD_1
	v_pk_mul_f16 v19, v22, v18
	v_pk_mul_f16 v21, v26, v20
	v_fma_mix_f32 v18, v19, v2, 0 op_sel_hi:[1,0,0]
	v_fma_mix_f32 v19, v19, v3, 0 op_sel:[1,0,0] op_sel_hi:[1,0,0]
	v_cvt_pk_bf16_f32 v2, v10, v11
	v_add_u32_e32 v10, 0xb0, v224
	v_mad_i64_i32 v[10:11], s[18:19], v10, s38, v[98:99]
	v_fma_mix_f32 v20, v21, v4, 0 op_sel_hi:[1,0,0]
	v_fma_mix_f32 v21, v21, v5, 0 op_sel:[1,0,0] op_sel_hi:[1,0,0]
	v_cvt_pk_bf16_f32 v3, v12, v13
	v_cvt_pk_bf16_f32 v4, v18, v19
	v_cvt_pk_bf16_f32 v5, v20, v21
	v_lshl_add_u64 v[10:11], v[10:11], 0, v[100:101]
	global_store_dwordx4 v[10:11], v[2:5], off
	s_and_saveexec_b64 s[18:19], s[78:79]
	s_cbranch_execz .LBB0_243
	v_add_u32_e32 v4, -14, v223
	v_mov_b64_e32 v[2:3], s[64:65]
	s_movk_i32 s12, 0x2c00
	v_mad_i64_i32 v[2:3], s[20:21], v4, s12, v[2:3]
	v_lshl_add_u64 v[2:3], v[194:195], 2, v[2:3]
	global_store_dwordx4 v[2:3], v[14:17], off
	global_store_dwordx4 v[2:3], v[6:9], off offset:16
